# LayerNorm row loops: mean/variance 64-lane butterfly sums via DPP and permlane swaps instead of 12 serialized ds_bpermute round trips per row (f32, summation order only)
# baseline (speedup 1.0000x reference)
.LBB0_298:
	v_lshl_add_u64 v[0:1], v[16:17], 0, v[10:11]
	global_load_dwordx4 v[28:31], v[0:1], off
	global_load_dwordx4 v[32:35], v[0:1], off offset:1024
	global_load_dwordx4 v[4:7], v[0:1], off offset:2048
	s_nop 0
	global_load_dwordx4 v[0:3], v[0:1], off offset:3072
	s_nop 0
	v_lshl_add_u64 v[44:45], v[20:21], 0, v[10:11]
	v_add_u32_e32 v8, s6, v8
	v_lshl_add_u64 v[16:17], v[16:17], 0, s[8:9]
	v_lshl_add_u64 v[20:21], v[20:21], 0, s[8:9]
	s_waitcnt vmcnt(3)
	v_mov_b32_e32 v46, v29
	v_mov_b32_e32 v47, v30
	v_mov_b32_e32 v48, v28
	v_mov_b32_e32 v49, v31
	s_waitcnt vmcnt(2)
	v_mov_b32_e32 v50, v33
	v_mov_b32_e32 v51, v34
	v_mov_b32_e32 v52, v32
	v_mov_b32_e32 v53, v35
	v_pk_add_f32 v[46:47], v[46:47], v[48:49]
	v_pk_add_f32 v[48:49], v[50:51], v[52:53]
	v_add_f32_e32 v52, v46, v47
	v_pk_add_f32 v[46:47], v[48:49], v[48:49] op_sel:[0,1] op_sel_hi:[1,0]
	s_waitcnt vmcnt(1)
	v_add_f32_e32 v54, v4, v5
	v_add_f32_e32 v56, v6, v7
	s_waitcnt vmcnt(0)
	v_mov_b32_e32 v59, v0
	v_mov_b32_e32 v55, v2
	v_mov_b32_e32 v57, v3
	v_add_f32_e32 v58, 0, v52
	v_mov_b32_e32 v47, v1
	v_pk_add_f32 v[50:51], v[54:55], v[56:57]
	v_pk_add_f32 v[46:47], v[58:59], v[46:47]
	s_nop 0
	v_pk_add_f32 v[46:47], v[46:47], v[50:51]
	s_nop 0
	v_add_f32_e32 v46, v46, v47
	s_nop 1
	v_add_f32_dpp v46, v46, v46 quad_perm:[1,0,3,2] row_mask:0xf bank_mask:0xf
	s_nop 1
	v_add_f32_dpp v46, v46, v46 quad_perm:[2,3,0,1] row_mask:0xf bank_mask:0xf
	s_nop 1
	v_add_f32_dpp v46, v46, v46 row_half_mirror row_mask:0xf bank_mask:0xf
	s_nop 1
	v_add_f32_dpp v46, v46, v46 row_mirror row_mask:0xf bank_mask:0xf
	v_mov_b32_e32 v47, v46
	s_nop 1
	v_permlane16_swap_b32_e32 v46, v47
	v_add_f32_e32 v46, v46, v47
	v_mov_b32_e32 v47, v46
	s_nop 1
	v_permlane32_swap_b32_e32 v46, v47
	v_add_f32_e32 v50, v46, v47
	v_fmamk_f32 v29, v50, 0xba800000, v29
	v_fmamk_f32 v28, v50, 0xba800000, v28
	v_fmamk_f32 v31, v50, 0xba800000, v31
	v_fmac_f32_e32 v30, 0xba800000, v50
	v_fmamk_f32 v33, v50, 0xba800000, v33
	v_fmamk_f32 v32, v50, 0xba800000, v32
	v_fmamk_f32 v35, v50, 0xba800000, v35
	v_fmac_f32_e32 v34, 0xba800000, v50
	v_fmamk_f32 v47, v50, 0xba800000, v5
	v_fmamk_f32 v46, v50, 0xba800000, v4
	v_fmamk_f32 v7, v50, 0xba800000, v7
	v_fmac_f32_e32 v6, 0xba800000, v50
	v_fmamk_f32 v49, v50, 0xba800000, v3
	v_fmamk_f32 v48, v50, 0xba800000, v2
	v_fmamk_f32 v1, v50, 0xba800000, v1
	v_fmac_f32_e32 v0, 0xba800000, v50
	v_pk_mul_f32 v[2:3], v[30:31], v[30:31]
	v_pk_mul_f32 v[4:5], v[28:29], v[28:29]
	v_pk_mul_f32 v[50:51], v[34:35], v[34:35]
	v_pk_mul_f32 v[52:53], v[32:33], v[32:33]
	v_pk_mov_b32 v[58:59], v[4:5], v[2:3] op_sel:[1,0]
	v_mov_b32_e32 v5, v3
	v_pk_mov_b32 v[2:3], v[52:53], v[50:51] op_sel:[1,0]
	v_mov_b32_e32 v53, v51
	v_mul_f32_e32 v54, v46, v46
	v_mul_f32_e32 v56, v6, v6
	v_pk_add_f32 v[4:5], v[58:59], v[4:5]
	v_pk_add_f32 v[2:3], v[2:3], v[52:53]
	v_pk_fma_f32 v[50:51], v[46:47], v[46:47], v[54:55] op_sel_hi:[1,1,0]
	v_pk_fma_f32 v[54:55], v[6:7], v[6:7], v[56:57] op_sel_hi:[1,1,0]
	v_pk_add_f32 v[4:5], v[4:5], v[4:5] op_sel_hi:[0,1]
	v_pk_add_f32 v[2:3], v[2:3], v[2:3] op_sel_hi:[0,1]
	v_mul_f32_e32 v50, v0, v0
	v_mul_f32_e32 v54, v1, v1
	v_mul_f32_e32 v4, v48, v48
	v_mul_f32_e32 v2, v49, v49
	v_pk_add_f32 v[50:51], v[50:51], v[54:55]
	v_pk_add_f32 v[2:3], v[4:5], v[2:3]
	s_nop 0
	v_pk_add_f32 v[2:3], v[50:51], v[2:3]
	s_nop 0
	v_add_f32_e32 v2, v2, v3
	s_nop 1
	v_add_f32_dpp v2, v2, v2 quad_perm:[1,0,3,2] row_mask:0xf bank_mask:0xf
	s_nop 1
	v_add_f32_dpp v2, v2, v2 quad_perm:[2,3,0,1] row_mask:0xf bank_mask:0xf
	s_nop 1
	v_add_f32_dpp v2, v2, v2 row_half_mirror row_mask:0xf bank_mask:0xf
	s_nop 1
	v_add_f32_dpp v2, v2, v2 row_mirror row_mask:0xf bank_mask:0xf
	v_mov_b32_e32 v3, v2
	s_nop 1
	v_permlane16_swap_b32_e32 v2, v3
	v_add_f32_e32 v2, v2, v3
	v_mov_b32_e32 v3, v2
	s_nop 1
	v_permlane32_swap_b32_e32 v2, v3
	v_add_f32_e32 v2, v2, v3
	v_fmamk_f32 v2, v2, 0x3a800000, v9
	v_mul_f32_e32 v3, 0x4b800000, v2
	v_cmp_gt_f32_e32 vcc, s3, v2
	s_nop 1
	v_cndmask_b32_e32 v2, v2, v3, vcc
	v_rsq_f32_e32 v2, v2
	s_nop 0
	v_mul_f32_e32 v3, 0x45800000, v2
	v_cndmask_b32_e32 v50, v2, v3, vcc
	v_pk_mul_f32 v[2:3], v[28:29], v[50:51] op_sel_hi:[1,0]
	v_pk_mul_f32 v[4:5], v[30:31], v[50:51] op_sel_hi:[1,0]
	s_nop 1
	v_pk_fma_f32 v[2:3], v[200:201], v[2:3], v[216:217]
	v_pk_fma_f32 v[4:5], v[202:203], v[4:5], v[218:219]
	global_store_dwordx4 v[44:45], v[2:5], off
	v_pk_mul_f32 v[34:35], v[34:35], v[50:51] op_sel_hi:[1,0]
	v_pk_mul_f32 v[32:33], v[32:33], v[50:51] op_sel_hi:[1,0]
	v_cvt_pk_bf16_f32 v2, v2, v3
	v_cvt_pk_bf16_f32 v3, v4, v5
	global_store_dwordx2 v[18:19], v[2:3], off offset:-1024
	s_nop 0
	v_pk_mul_f32 v[6:7], v[6:7], v[50:51] op_sel_hi:[1,0]
	v_pk_mul_f32 v[0:1], v[0:1], v[50:51] op_sel_hi:[1,0]
	v_cmp_lt_i32_e32 vcc, s7, v8
	s_or_b64 s[12:13], vcc, s[12:13]
	s_nop 1
	v_pk_fma_f32 v[2:3], v[204:205], v[32:33], v[220:221]
	v_pk_fma_f32 v[4:5], v[206:207], v[34:35], v[222:223]
	global_store_dwordx4 v[44:45], v[2:5], off offset:1024
	v_pk_mul_f32 v[32:33], v[46:47], v[50:51] op_sel_hi:[1,0]
	s_nop 0
	v_cvt_pk_bf16_f32 v2, v2, v3
	v_cvt_pk_bf16_f32 v3, v4, v5
	global_store_dwordx2 v[18:19], v[2:3], off offset:-512
	s_nop 0
	s_nop 1
	v_pk_fma_f32 v[2:3], v[208:209], v[32:33], v[224:225]
	v_pk_fma_f32 v[4:5], v[210:211], v[6:7], v[226:227]
	global_store_dwordx4 v[44:45], v[2:5], off offset:2048
	v_pk_mul_f32 v[6:7], v[48:49], v[50:51] op_sel_hi:[1,0]
	s_nop 0
	v_cvt_pk_bf16_f32 v2, v2, v3
	v_cvt_pk_bf16_f32 v3, v4, v5
	global_store_dwordx2 v[18:19], v[2:3], off
	s_nop 0
	s_nop 1
	v_pk_fma_f32 v[0:1], v[212:213], v[0:1], v[228:229]
	v_pk_fma_f32 v[2:3], v[214:215], v[6:7], v[230:231]
	global_store_dwordx4 v[44:45], v[0:3], off offset:3072
	s_nop 1
	v_cvt_pk_bf16_f32 v0, v0, v1
	v_cvt_pk_bf16_f32 v1, v2, v3
	global_store_dwordx2 v[18:19], v[0:1], off offset:512
	v_lshl_add_u64 v[18:19], v[18:19], 0, s[10:11]
	s_andn2_b64 exec, exec, s[12:13]
	s_cbranch_execnz .LBB0_298
